# code placement: 15 s_nop in front of the G2 K-loop preheader so the four GEMM K-loop headers sit at the byte offsets (mod 128) they had in the SGU version
# speedup vs baseline: 1.0024x; 1.0020x over previous
;     __host__ __device__ bool next(int i, Unit& u) const {
;         const int xcd = c & 7, j = c >> 3, L = 256 * i + (8 * (xcd & 1) + (j >> 2)) * 16 + 4 * (xcd >> 1) + (j & 3);
;         if (L >= nU) return false;
;         const int rb = L / (16 * nN), rem = L - rb * 16 * nN;
;         u.pm = 16 * rb + (rem & 15); u.pn = rem >> 4; return true;
;     ...
;         const bool has_next = S.next(ui + 1, nxt);
;         const char* nA = has_next ? (const char*)g.A + (size_t)nxt.pm * tstepA : cA; const char* nB = has_next ? (const char*)g.Bt + (size_t)nxt.pn * tstepB : cB;
.LBB0_555:
	s_add_i32 s72, s72, 1
	s_lshl_b32 s6, s72, 8
	s_add_i32 s6, s6, s70
	s_or_b32 s7, s6, s71
	s_cmpk_lt_i32 s7, 0x400
	s_cselect_b64 s[26:27], -1, 0
	s_cmpk_gt_i32 s7, 0x3ff
	s_cbranch_scc1 .LBB0_557
	s_ashr_i32 s16, s7, 31
	s_lshr_b32 s16, s16, 24
	s_add_i32 s7, s7, s16
	s_ashr_i32 s16, s7, 8
	s_and_b32 s7, s7, 0xffffff00
	s_lshl_b32 s16, s16, 4
	s_sub_i32 s6, s6, s7
	s_or_b32 s20, s16, s71
	s_ashr_i32 s22, s6, 4
	s_nop 0
	s_nop 0
	s_nop 0
	s_nop 0
	s_nop 0
	s_nop 0
	s_nop 0
	s_nop 0
	s_nop 0
	s_nop 0
	s_nop 0
	s_nop 0
	s_nop 0
	s_nop 0
	s_nop 0
